# code placement: every GEMM K-loop head padded back to its baseline phase mod 8 (s_nop pads outside the loops)
# baseline (speedup 1.0000x reference)
.LBB0_332:
	s_ashr_i32 s49, s48, 31
	s_lshl_b64 s[18:19], s[48:49], 9
	v_readlane_b32 s33, v253, 24
	s_add_u32 s50, s33, s18
	v_readlane_b32 s18, v253, 25
	s_addc_u32 s51, s18, s19
	s_and_b64 s[18:19], s[42:43], exec
	s_cselect_b32 s18, s51, s57
	s_cselect_b32 s19, s50, s56
	s_ashr_i32 s45, s44, 31
	s_lshl_b64 s[52:53], s[44:45], 17
	v_readlane_b32 s58, v253, 20
	v_readlane_b32 s59, v253, 21
	s_add_u32 s52, s58, s52
	s_addc_u32 s53, s59, s53
	s_and_b64 s[58:59], s[42:43], exec
	v_mov_b32_e32 v2, 0
	s_cselect_b32 s33, s53, s55
	s_cselect_b32 s45, s52, s54
	s_mov_b32 s49, 0
	s_mov_b64 s[58:59], -1
	s_mov_b64 s[60:61], 0
	v_mov_b32_e32 v3, v2
	v_mov_b32_e32 v4, v2
	v_mov_b32_e32 v5, v2
	v_mov_b32_e32 v6, v2
	v_mov_b32_e32 v7, v2
	v_mov_b32_e32 v8, v2
	v_mov_b32_e32 v9, v2
	v_mov_b32_e32 v10, v2
	v_mov_b32_e32 v11, v2
	v_mov_b32_e32 v12, v2
	v_mov_b32_e32 v13, v2
	v_mov_b32_e32 v14, v2
	v_mov_b32_e32 v15, v2
	v_mov_b32_e32 v16, v2
	v_mov_b32_e32 v17, v2
	v_mov_b32_e32 v26, v2
	v_mov_b32_e32 v27, v2
	v_mov_b32_e32 v28, v2
	v_mov_b32_e32 v29, v2
	v_mov_b32_e32 v30, v2
	v_mov_b32_e32 v31, v2
	v_mov_b32_e32 v32, v2
	v_mov_b32_e32 v33, v2
	v_mov_b32_e32 v42, v2
	v_mov_b32_e32 v43, v2
	v_mov_b32_e32 v44, v2
	v_mov_b32_e32 v45, v2
	v_mov_b32_e32 v46, v2
	v_mov_b32_e32 v47, v2
	v_mov_b32_e32 v48, v2
	v_mov_b32_e32 v49, v2
	v_mov_b32_e32 v18, v2
	v_mov_b32_e32 v19, v2
	v_mov_b32_e32 v20, v2
	v_mov_b32_e32 v21, v2
	v_mov_b32_e32 v22, v2
	v_mov_b32_e32 v23, v2
	v_mov_b32_e32 v24, v2
	v_mov_b32_e32 v25, v2
	v_mov_b32_e32 v34, v2
	v_mov_b32_e32 v35, v2
	v_mov_b32_e32 v36, v2
	v_mov_b32_e32 v37, v2
	v_mov_b32_e32 v38, v2
	v_mov_b32_e32 v39, v2
	v_mov_b32_e32 v40, v2
	v_mov_b32_e32 v41, v2
	v_mov_b32_e32 v50, v2
	v_mov_b32_e32 v51, v2
	v_mov_b32_e32 v52, v2
	v_mov_b32_e32 v53, v2
	v_mov_b32_e32 v54, v2
	v_mov_b32_e32 v55, v2
	v_mov_b32_e32 v56, v2
	v_mov_b32_e32 v57, v2
	v_mov_b32_e32 v58, v2
	v_mov_b32_e32 v59, v2
	v_mov_b32_e32 v60, v2
	v_mov_b32_e32 v61, v2
	v_mov_b32_e32 v62, v2
	v_mov_b32_e32 v63, v2
	v_mov_b32_e32 v64, v2
	v_mov_b32_e32 v65, v2
	v_mov_b32_e32 v66, v2
	v_mov_b32_e32 v67, v2
	v_mov_b32_e32 v68, v2
	v_mov_b32_e32 v69, v2
	v_mov_b32_e32 v70, v2
	v_mov_b32_e32 v71, v2
	v_mov_b32_e32 v72, v2
	v_mov_b32_e32 v73, v2
	v_mov_b32_e32 v74, v2
	v_mov_b32_e32 v75, v2
	v_mov_b32_e32 v76, v2
	v_mov_b32_e32 v77, v2
	v_mov_b32_e32 v78, v2
	v_mov_b32_e32 v79, v2
	v_mov_b32_e32 v80, v2
	v_mov_b32_e32 v81, v2
	v_mov_b32_e32 v90, v2
	v_mov_b32_e32 v91, v2
	v_mov_b32_e32 v92, v2
	v_mov_b32_e32 v93, v2
	v_mov_b32_e32 v94, v2
	v_mov_b32_e32 v95, v2
	v_mov_b32_e32 v96, v2
	v_mov_b32_e32 v97, v2
	v_mov_b32_e32 v108, v2
	v_mov_b32_e32 v109, v2
	v_mov_b32_e32 v110, v2
	v_mov_b32_e32 v111, v2
	v_mov_b32_e32 v112, v2
	v_mov_b32_e32 v113, v2
	v_mov_b32_e32 v114, v2
	v_mov_b32_e32 v115, v2
	v_mov_b32_e32 v82, v2
	v_mov_b32_e32 v83, v2
	v_mov_b32_e32 v84, v2
	v_mov_b32_e32 v85, v2
	v_mov_b32_e32 v86, v2
	v_mov_b32_e32 v87, v2
	v_mov_b32_e32 v88, v2
	v_mov_b32_e32 v89, v2
	v_mov_b32_e32 v100, v2
	v_mov_b32_e32 v101, v2
	v_mov_b32_e32 v102, v2
	v_mov_b32_e32 v103, v2
	v_mov_b32_e32 v104, v2
	v_mov_b32_e32 v105, v2
	v_mov_b32_e32 v106, v2
	v_mov_b32_e32 v107, v2
	v_mov_b32_e32 v116, v2
	v_mov_b32_e32 v117, v2
	v_mov_b32_e32 v118, v2
	v_mov_b32_e32 v119, v2
	v_mov_b32_e32 v120, v2
	v_mov_b32_e32 v121, v2
	v_mov_b32_e32 v122, v2
	v_mov_b32_e32 v123, v2
	v_mov_b32_e32 v124, v2
	v_mov_b32_e32 v125, v2
	v_mov_b32_e32 v126, v2
	v_mov_b32_e32 v127, v2
	v_mov_b32_e32 v128, v2
	v_mov_b32_e32 v129, v2
	v_mov_b32_e32 v130, v2
	v_mov_b32_e32 v131, v2
	s_nop 0

.LBB0_646:
	s_ashr_i32 s49, s48, 31
	s_lshl_b64 s[52:53], s[48:49], 12
	s_add_u32 s49, s92, s52
	s_addc_u32 s53, s93, s53
	s_lshl_b32 s52, s59, 1
	s_ashr_i32 s63, s52, 31
	s_add_u32 s52, s49, s52
	s_addc_u32 s53, s53, s63
	s_and_b64 s[54:55], s[54:55], exec
	s_cselect_b32 s49, s53, s41
	s_cselect_b32 s63, s52, s40
	s_add_i32 s65, s62, -2
	s_add_u32 s40, s40, 0x80080
	s_addc_u32 s41, s41, 0
	s_add_u32 s66, s42, 0x100
	v_mov_b32_e32 v2, 0
	s_addc_u32 s67, s43, 0
	s_mov_b32 s42, 0
	v_mov_b32_e32 v3, v2
	v_mov_b32_e32 v4, v2
	v_mov_b32_e32 v5, v2
	v_mov_b32_e32 v6, v2
	v_mov_b32_e32 v7, v2
	v_mov_b32_e32 v8, v2
	v_mov_b32_e32 v9, v2
	v_mov_b32_e32 v18, v2
	v_mov_b32_e32 v19, v2
	v_mov_b32_e32 v20, v2
	v_mov_b32_e32 v21, v2
	v_mov_b32_e32 v22, v2
	v_mov_b32_e32 v23, v2
	v_mov_b32_e32 v24, v2
	v_mov_b32_e32 v25, v2
	v_mov_b32_e32 v34, v2
	v_mov_b32_e32 v35, v2
	v_mov_b32_e32 v36, v2
	v_mov_b32_e32 v37, v2
	v_mov_b32_e32 v38, v2
	v_mov_b32_e32 v39, v2
	v_mov_b32_e32 v40, v2
	v_mov_b32_e32 v41, v2
	v_mov_b32_e32 v50, v2
	v_mov_b32_e32 v51, v2
	v_mov_b32_e32 v52, v2
	v_mov_b32_e32 v53, v2
	v_mov_b32_e32 v54, v2
	v_mov_b32_e32 v55, v2
	v_mov_b32_e32 v56, v2
	v_mov_b32_e32 v57, v2
	v_mov_b32_e32 v10, v2
	v_mov_b32_e32 v11, v2
	v_mov_b32_e32 v12, v2
	v_mov_b32_e32 v13, v2
	v_mov_b32_e32 v14, v2
	v_mov_b32_e32 v15, v2
	v_mov_b32_e32 v16, v2
	v_mov_b32_e32 v17, v2
	v_mov_b32_e32 v26, v2
	v_mov_b32_e32 v27, v2
	v_mov_b32_e32 v28, v2
	v_mov_b32_e32 v29, v2
	v_mov_b32_e32 v30, v2
	v_mov_b32_e32 v31, v2
	v_mov_b32_e32 v32, v2
	v_mov_b32_e32 v33, v2
	v_mov_b32_e32 v42, v2
	v_mov_b32_e32 v43, v2
	v_mov_b32_e32 v44, v2
	v_mov_b32_e32 v45, v2
	v_mov_b32_e32 v46, v2
	v_mov_b32_e32 v47, v2
	v_mov_b32_e32 v48, v2
	v_mov_b32_e32 v49, v2
	v_mov_b32_e32 v58, v2
	v_mov_b32_e32 v59, v2
	v_mov_b32_e32 v60, v2
	v_mov_b32_e32 v61, v2
	v_mov_b32_e32 v62, v2
	v_mov_b32_e32 v63, v2
	v_mov_b32_e32 v64, v2
	v_mov_b32_e32 v65, v2
	v_mov_b32_e32 v66, v2
	v_mov_b32_e32 v67, v2
	v_mov_b32_e32 v68, v2
	v_mov_b32_e32 v69, v2
	v_mov_b32_e32 v70, v2
	v_mov_b32_e32 v71, v2
	v_mov_b32_e32 v72, v2
	v_mov_b32_e32 v73, v2
	v_mov_b32_e32 v82, v2
	v_mov_b32_e32 v83, v2
	v_mov_b32_e32 v84, v2
	v_mov_b32_e32 v85, v2
	v_mov_b32_e32 v86, v2
	v_mov_b32_e32 v87, v2
	v_mov_b32_e32 v88, v2
	v_mov_b32_e32 v89, v2
	v_mov_b32_e32 v100, v2
	v_mov_b32_e32 v101, v2
	v_mov_b32_e32 v102, v2
	v_mov_b32_e32 v103, v2
	v_mov_b32_e32 v104, v2
	v_mov_b32_e32 v105, v2
	v_mov_b32_e32 v106, v2
	v_mov_b32_e32 v107, v2
	v_mov_b32_e32 v116, v2
	v_mov_b32_e32 v117, v2
	v_mov_b32_e32 v118, v2
	v_mov_b32_e32 v119, v2
	v_mov_b32_e32 v120, v2
	v_mov_b32_e32 v121, v2
	v_mov_b32_e32 v122, v2
	v_mov_b32_e32 v123, v2
	v_mov_b32_e32 v74, v2
	v_mov_b32_e32 v75, v2
	v_mov_b32_e32 v76, v2
	v_mov_b32_e32 v77, v2
	v_mov_b32_e32 v78, v2
	v_mov_b32_e32 v79, v2
	v_mov_b32_e32 v80, v2
	v_mov_b32_e32 v81, v2
	v_mov_b32_e32 v90, v2
	v_mov_b32_e32 v91, v2
	v_mov_b32_e32 v92, v2
	v_mov_b32_e32 v93, v2
	v_mov_b32_e32 v94, v2
	v_mov_b32_e32 v95, v2
	v_mov_b32_e32 v96, v2
	v_mov_b32_e32 v97, v2
	v_mov_b32_e32 v108, v2
	v_mov_b32_e32 v109, v2
	v_mov_b32_e32 v110, v2
	v_mov_b32_e32 v111, v2
	v_mov_b32_e32 v112, v2
	v_mov_b32_e32 v113, v2
	v_mov_b32_e32 v114, v2
	v_mov_b32_e32 v115, v2
	v_mov_b32_e32 v124, v2
	v_mov_b32_e32 v125, v2
	v_mov_b32_e32 v126, v2
	v_mov_b32_e32 v127, v2
	v_mov_b32_e32 v128, v2
	v_mov_b32_e32 v129, v2
	v_mov_b32_e32 v130, v2
	v_mov_b32_e32 v131, v2
	s_nop 0

.LBB0_892:
	s_ashr_i32 s39, s38, 31
	s_lshl_b64 s[42:43], s[38:39], 10
	v_readlane_b32 s19, v253, 43
	s_add_u32 s42, s19, s42
	v_readlane_b32 s19, v253, 44
	s_addc_u32 s43, s19, s43
	s_and_b64 s[44:45], s[40:41], exec
	s_cselect_b32 s19, s43, s49
	s_cselect_b32 s33, s42, s48
	s_ashr_i32 s37, s36, 31
	s_lshl_b64 s[44:45], s[36:37], 18
	v_readlane_b32 s37, v253, 39
	s_add_u32 s44, s37, s44
	v_readlane_b32 s37, v253, 40
	s_addc_u32 s45, s37, s45
	s_and_b64 s[52:53], s[40:41], exec
	s_cselect_b32 s37, s45, s51
	s_cselect_b32 s39, s44, s50
	s_add_u32 s48, s48, 0x20080
	s_addc_u32 s49, s49, 0
	s_add_u32 s54, s50, 0x100
	v_mov_b32_e32 v2, 0
	s_addc_u32 s55, s51, 0
	s_mov_b32 s56, -2
	v_mov_b32_e32 v3, v2
	v_mov_b32_e32 v4, v2
	v_mov_b32_e32 v5, v2
	v_mov_b32_e32 v6, v2
	v_mov_b32_e32 v7, v2
	v_mov_b32_e32 v8, v2
	v_mov_b32_e32 v9, v2
	v_mov_b32_e32 v18, v2
	v_mov_b32_e32 v19, v2
	v_mov_b32_e32 v20, v2
	v_mov_b32_e32 v21, v2
	v_mov_b32_e32 v22, v2
	v_mov_b32_e32 v23, v2
	v_mov_b32_e32 v24, v2
	v_mov_b32_e32 v25, v2
	v_mov_b32_e32 v34, v2
	v_mov_b32_e32 v35, v2
	v_mov_b32_e32 v36, v2
	v_mov_b32_e32 v37, v2
	v_mov_b32_e32 v38, v2
	v_mov_b32_e32 v39, v2
	v_mov_b32_e32 v40, v2
	v_mov_b32_e32 v41, v2
	v_mov_b32_e32 v50, v2
	v_mov_b32_e32 v51, v2
	v_mov_b32_e32 v52, v2
	v_mov_b32_e32 v53, v2
	v_mov_b32_e32 v54, v2
	v_mov_b32_e32 v55, v2
	v_mov_b32_e32 v56, v2
	v_mov_b32_e32 v57, v2
	v_mov_b32_e32 v10, v2
	v_mov_b32_e32 v11, v2
	v_mov_b32_e32 v12, v2
	v_mov_b32_e32 v13, v2
	v_mov_b32_e32 v14, v2
	v_mov_b32_e32 v15, v2
	v_mov_b32_e32 v16, v2
	v_mov_b32_e32 v17, v2
	v_mov_b32_e32 v26, v2
	v_mov_b32_e32 v27, v2
	v_mov_b32_e32 v28, v2
	v_mov_b32_e32 v29, v2
	v_mov_b32_e32 v30, v2
	v_mov_b32_e32 v31, v2
	v_mov_b32_e32 v32, v2
	v_mov_b32_e32 v33, v2
	v_mov_b32_e32 v42, v2
	v_mov_b32_e32 v43, v2
	v_mov_b32_e32 v44, v2
	v_mov_b32_e32 v45, v2
	v_mov_b32_e32 v46, v2
	v_mov_b32_e32 v47, v2
	v_mov_b32_e32 v48, v2
	v_mov_b32_e32 v49, v2
	v_mov_b32_e32 v58, v2
	v_mov_b32_e32 v59, v2
	v_mov_b32_e32 v60, v2
	v_mov_b32_e32 v61, v2
	v_mov_b32_e32 v62, v2
	v_mov_b32_e32 v63, v2
	v_mov_b32_e32 v64, v2
	v_mov_b32_e32 v65, v2
	v_mov_b32_e32 v66, v2
	v_mov_b32_e32 v67, v2
	v_mov_b32_e32 v68, v2
	v_mov_b32_e32 v69, v2
	v_mov_b32_e32 v70, v2
	v_mov_b32_e32 v71, v2
	v_mov_b32_e32 v72, v2
	v_mov_b32_e32 v73, v2
	v_mov_b32_e32 v82, v2
	v_mov_b32_e32 v83, v2
	v_mov_b32_e32 v84, v2
	v_mov_b32_e32 v85, v2
	v_mov_b32_e32 v86, v2
	v_mov_b32_e32 v87, v2
	v_mov_b32_e32 v88, v2
	v_mov_b32_e32 v89, v2
	v_mov_b32_e32 v100, v2
	v_mov_b32_e32 v101, v2
	v_mov_b32_e32 v102, v2
	v_mov_b32_e32 v103, v2
	v_mov_b32_e32 v104, v2
	v_mov_b32_e32 v105, v2
	v_mov_b32_e32 v106, v2
	v_mov_b32_e32 v107, v2
	v_mov_b32_e32 v116, v2
	v_mov_b32_e32 v117, v2
	v_mov_b32_e32 v118, v2
	v_mov_b32_e32 v119, v2
	v_mov_b32_e32 v120, v2
	v_mov_b32_e32 v121, v2
	v_mov_b32_e32 v122, v2
	v_mov_b32_e32 v123, v2
	v_mov_b32_e32 v74, v2
	v_mov_b32_e32 v75, v2
	v_mov_b32_e32 v76, v2
	v_mov_b32_e32 v77, v2
	v_mov_b32_e32 v78, v2
	v_mov_b32_e32 v79, v2
	v_mov_b32_e32 v80, v2
	v_mov_b32_e32 v81, v2
	v_mov_b32_e32 v90, v2
	v_mov_b32_e32 v91, v2
	v_mov_b32_e32 v92, v2
	v_mov_b32_e32 v93, v2
	v_mov_b32_e32 v94, v2
	v_mov_b32_e32 v95, v2
	v_mov_b32_e32 v96, v2
	v_mov_b32_e32 v97, v2
	v_mov_b32_e32 v108, v2
	v_mov_b32_e32 v109, v2
	v_mov_b32_e32 v110, v2
	v_mov_b32_e32 v111, v2
	v_mov_b32_e32 v112, v2
	v_mov_b32_e32 v113, v2
	v_mov_b32_e32 v114, v2
	v_mov_b32_e32 v115, v2
	v_mov_b32_e32 v124, v2
	v_mov_b32_e32 v125, v2
	v_mov_b32_e32 v126, v2
	v_mov_b32_e32 v127, v2
	v_mov_b32_e32 v128, v2
	v_mov_b32_e32 v129, v2
	v_mov_b32_e32 v130, v2
	v_mov_b32_e32 v131, v2
	s_nop 0
